# attention QK^T: 8 K fragments per tile read up front into dead registers, MFMA chain waits on counted lgkmcnt
# speedup vs baseline: 1.0015x; 1.0015x over previous
.LBB0_1131:
	s_ashr_i32 s44, s58, 6
	s_and_b32 s4, s58, 63
	s_add_i32 s46, s44, s10
	s_lshr_b32 s47, s4, s62
	s_and_b32 s5, s4, s63
	s_add_i32 s4, s11, s46
	s_waitcnt vmcnt(16)
	v_cvt_f32_i32_e32 v0, s4
	s_lshl_b32 s61, s5, 8
	v_readlane_b32 s4, v253, 56
	s_ashr_i32 s45, s44, 31
	v_mul_f32_e32 v0, 0xbe2aaaab, v0
	v_exp_f32_e32 v0, v0
	s_add_i32 s4, s61, s4
	s_lshl_b64 s[12:13], s[44:45], 14
	s_mul_i32 s45, s47, s41
	s_add_u32 s12, s12, s45
	v_or_b32_e32 v138, s4, v150
	s_addc_u32 s13, s13, 0
	v_mul_f32_e32 v2, v0, v152
	v_lshl_add_u64 v[0:1], s[12:13], 0, v[138:139]
	v_lshlrev_b64 v[0:1], 8, v[0:1]
	s_waitcnt vmcnt(8)
	v_mov_b32_e32 v93, v158
	v_lshl_add_u64 v[0:1], v[132:133], 0, v[0:1]
	global_load_dwordx4 v[44:47], v[0:1], off
	global_load_dwordx4 v[40:43], v[0:1], off offset:32
	global_load_dwordx4 v[36:39], v[0:1], off offset:64
	global_load_dwordx4 v[32:35], v[0:1], off offset:96
	global_load_dwordx4 v[28:31], v[0:1], off offset:128
	global_load_dwordx4 v[24:27], v[0:1], off offset:160
	global_load_dwordx4 v[20:23], v[0:1], off offset:192
	global_load_dwordx4 v[16:19], v[0:1], off offset:224
	s_cmpk_gt_u32 s4, 0x7f
	s_mov_b32 s50, s94
	v_mul_f32_e32 v92, 0x3fb8aa3b, v2
	v_mov_b32_e32 v48, 0xf149f2ca
	s_cselect_b64 s[48:49], -1, 0
	s_cmpk_lt_u32 s4, 0x80
	v_mov_b32_e32 v84, 0xf149f2ca
	v_mov_b32_e32 v85, 0xf149f2ca
	v_mov_b32_e32 v100, 0xf149f2ca
	v_mov_b32_e32 v102, 0xf149f2ca
	v_mov_b32_e32 v101, 0xf149f2ca
	v_mov_b32_e32 v104, 0xf149f2ca
	v_mov_b32_e32 v103, 0xf149f2ca
	v_mov_b32_e32 v106, 0xf149f2ca
	v_mov_b32_e32 v105, 0xf149f2ca
	v_mov_b32_e32 v108, 0xf149f2ca
	v_mov_b32_e32 v107, 0xf149f2ca
	v_mov_b32_e32 v110, 0xf149f2ca
	v_mov_b32_e32 v109, 0xf149f2ca
	v_mov_b32_e32 v112, 0xf149f2ca
	v_mov_b32_e32 v111, 0xf149f2ca
	v_mov_b32_e32 v114, 0xf149f2ca
	v_mov_b32_e32 v113, 0xf149f2ca
	s_waitcnt lgkmcnt(0)
	s_barrier
	s_cbranch_scc1 .LBB0_1133
	ds_read_b128 v[220:223], v163
	ds_read_b128 v[224:227], v164
	ds_read_b128 v[228:231], v165
	ds_read_b128 v[232:235], v166
	ds_read_b128 v[236:239], v167
	ds_read_b128 v[240:243], v168
	ds_read_b128 v[244:247], v169
	ds_read_b128 v[248:251], v170
	s_mov_b32 s12, 2.0
	s_mov_b32 s13, 0x40400000
	v_cmp_gt_i32_e32 vcc, s67, v93
	s_waitcnt vmcnt(7) lgkmcnt(7)
	v_mfma_f32_32x32x16_bf16 v[0:15], v[220:223], v[44:47], 0
	s_waitcnt vmcnt(6) lgkmcnt(6)
	v_mfma_f32_32x32x16_bf16 v[0:15], v[224:227], v[40:43], v[0:15]
	s_waitcnt vmcnt(5) lgkmcnt(5)
	v_mfma_f32_32x32x16_bf16 v[0:15], v[228:231], v[36:39], v[0:15]
	s_waitcnt vmcnt(4) lgkmcnt(4)
	v_mfma_f32_32x32x16_bf16 v[0:15], v[232:235], v[32:35], v[0:15]
	s_waitcnt vmcnt(3) lgkmcnt(3)
	v_mfma_f32_32x32x16_bf16 v[0:15], v[236:239], v[28:31], v[0:15]
	s_waitcnt vmcnt(2) lgkmcnt(2)
	v_mfma_f32_32x32x16_bf16 v[0:15], v[240:243], v[24:27], v[0:15]
	s_waitcnt vmcnt(1) lgkmcnt(1)
	v_mfma_f32_32x32x16_bf16 v[0:15], v[244:247], v[20:23], v[0:15]
	s_waitcnt vmcnt(0) lgkmcnt(0)
	v_mfma_f32_32x32x16_bf16 v[0:15], v[248:251], v[16:19], v[0:15]
	s_nop 11
	v_pk_fma_f32 v[2:3], v[92:93], s[12:13], v[2:3] op_sel_hi:[0,1,1]
	s_mov_b32 s12, 0x41000000
	s_mov_b32 s13, 0x41100000
	v_pk_fma_f32 v[4:5], v[92:93], s[12:13], v[4:5] op_sel_hi:[0,1,1]
	s_mov_b32 s12, 0x41200000
	s_mov_b32 s13, 0x41300000
	v_pk_fma_f32 v[6:7], v[92:93], s[12:13], v[6:7] op_sel_hi:[0,1,1]
	s_mov_b32 s12, 0x41800000
	s_mov_b32 s13, 0x41880000
	v_pk_fma_f32 v[8:9], v[92:93], s[12:13], v[8:9] op_sel_hi:[0,1,1]
	s_mov_b32 s12, 0x41900000
	s_mov_b32 s13, 0x41980000
	v_pk_fma_f32 v[10:11], v[92:93], s[12:13], v[10:11] op_sel_hi:[0,1,1]
	s_mov_b32 s12, 0x41c00000
	s_mov_b32 s13, 0x41c80000
	v_pk_fma_f32 v[12:13], v[92:93], s[12:13], v[12:13] op_sel_hi:[0,1,1]
	s_mov_b32 s12, 0x41d00000
	s_mov_b32 s13, 0x41d80000
	v_fma_f32 v49, 0, v92, v0
	v_add_f32_e32 v50, v92, v1
	v_pk_fma_f32 v[0:1], v[92:93], s[12:13], v[14:15] op_sel_hi:[0,1,1]
	s_movk_i32 s12, 0x82
	v_cndmask_b32_e32 v85, v175, v49, vcc
	v_cmp_gt_i32_e32 vcc, s12, v93
	s_movk_i32 s12, 0x84
	s_nop 0
	v_cndmask_b32_e32 v100, v175, v50, vcc
	v_cmp_gt_i32_e32 vcc, s12, v93
	s_movk_i32 s12, 0x83
	s_nop 0
	v_cndmask_b32_e32 v101, v175, v3, vcc
	v_cmp_gt_i32_e32 vcc, s12, v93
	s_movk_i32 s12, 0x8a
	s_nop 0
	v_cndmask_b32_e32 v102, v175, v2, vcc
	v_cmp_gt_i32_e32 vcc, s12, v93
	s_movk_i32 s12, 0x89
	s_nop 0
	v_cndmask_b32_e32 v103, v175, v5, vcc
	v_cmp_gt_i32_e32 vcc, s12, v93
	s_movk_i32 s12, 0x8c
	s_nop 0
	v_cndmask_b32_e32 v104, v175, v4, vcc
	v_cmp_gt_i32_e32 vcc, s12, v93
	s_movk_i32 s12, 0x8b
	s_nop 0
	v_cndmask_b32_e32 v105, v175, v7, vcc
	v_cmp_gt_i32_e32 vcc, s12, v93
	s_movk_i32 s12, 0x92
	s_nop 0
	v_cndmask_b32_e32 v106, v175, v6, vcc
	v_cmp_gt_i32_e32 vcc, s12, v93
	s_movk_i32 s12, 0x91
	s_nop 0
	v_cndmask_b32_e32 v107, v175, v9, vcc
	v_cmp_gt_i32_e32 vcc, s12, v93
	s_movk_i32 s12, 0x94
	s_nop 0
	v_cndmask_b32_e32 v108, v175, v8, vcc
	v_cmp_gt_i32_e32 vcc, s12, v93
	s_movk_i32 s12, 0x93
	s_nop 0
	v_cndmask_b32_e32 v109, v175, v11, vcc
	v_cmp_gt_i32_e32 vcc, s12, v93
	s_movk_i32 s12, 0x9a
	s_nop 0
	v_cndmask_b32_e32 v110, v175, v10, vcc
	v_cmp_gt_i32_e32 vcc, s12, v93
	s_movk_i32 s12, 0x99
	s_nop 0
	v_cndmask_b32_e32 v111, v175, v13, vcc
	v_cmp_gt_i32_e32 vcc, s12, v93
	s_movk_i32 s12, 0x9c
	s_nop 0
	v_cndmask_b32_e32 v112, v175, v12, vcc
	v_cmp_gt_i32_e32 vcc, s12, v93
	s_mov_b32 s12, 0xf149f2ca
	s_nop 0
	v_cndmask_b32_e32 v113, v175, v1, vcc
	v_max3_f32 v1, v85, s12, v100
	v_max3_f32 v1, v1, v102, v101
	v_max3_f32 v1, v1, v104, v103
	v_max3_f32 v1, v1, v106, v105
	v_max3_f32 v1, v1, v108, v107
	s_movk_i32 s12, 0x9b
	v_max3_f32 v1, v1, v110, v109
	v_cmp_gt_i32_e32 vcc, s12, v93
	v_max3_f32 v1, v1, v112, v111
	s_nop 0
	v_cndmask_b32_e32 v114, v175, v0, vcc
	v_max3_f32 v84, v1, v114, v113
.LBB0_1133:
	s_cmpk_gt_u32 s4, 0x5f
	s_cselect_b64 s[94:95], -1, 0
	s_cmpk_lt_u32 s4, 0x60
	s_cbranch_scc1 .LBB0_1135
	ds_read_b128 v[220:223], v163 offset:8192
	ds_read_b128 v[224:227], v164 offset:8192
	ds_read_b128 v[228:231], v165 offset:8192
	ds_read_b128 v[232:235], v166 offset:8192
	ds_read_b128 v[236:239], v167 offset:8192
	ds_read_b128 v[240:243], v168 offset:8192
	ds_read_b128 v[244:247], v169 offset:8192
	ds_read_b128 v[248:251], v170 offset:8192
	s_mov_b32 s12, 0x42000000
	s_mov_b32 s13, 0x42040000
	s_waitcnt vmcnt(7) lgkmcnt(7)
	v_mfma_f32_32x32x16_bf16 v[0:15], v[220:223], v[44:47], 0
	s_waitcnt vmcnt(6) lgkmcnt(6)
	v_mfma_f32_32x32x16_bf16 v[0:15], v[224:227], v[40:43], v[0:15]
	s_waitcnt vmcnt(5) lgkmcnt(5)
	v_mfma_f32_32x32x16_bf16 v[0:15], v[228:231], v[36:39], v[0:15]
	s_waitcnt vmcnt(4) lgkmcnt(4)
	v_mfma_f32_32x32x16_bf16 v[0:15], v[232:235], v[32:35], v[0:15]
	s_waitcnt vmcnt(3) lgkmcnt(3)
	v_mfma_f32_32x32x16_bf16 v[0:15], v[236:239], v[28:31], v[0:15]
	s_waitcnt vmcnt(2) lgkmcnt(2)
	v_mfma_f32_32x32x16_bf16 v[0:15], v[240:243], v[24:27], v[0:15]
	s_waitcnt vmcnt(1) lgkmcnt(1)
	v_mfma_f32_32x32x16_bf16 v[0:15], v[244:247], v[20:23], v[0:15]
	s_waitcnt vmcnt(0) lgkmcnt(0)
	v_mfma_f32_32x32x16_bf16 v[0:15], v[248:251], v[16:19], v[0:15]
	s_nop 11
	v_pk_fma_f32 v[48:49], v[92:93], s[12:13], v[0:1] op_sel_hi:[0,1,1]
	s_mov_b32 s12, 0x42080000
	s_mov_b32 s13, 0x420c0000
	v_pk_fma_f32 v[50:51], v[92:93], s[12:13], v[2:3] op_sel_hi:[0,1,1]
	s_mov_b32 s12, 0x42200000
	s_mov_b32 s13, 0x42240000
	v_pk_fma_f32 v[52:53], v[92:93], s[12:13], v[4:5] op_sel_hi:[0,1,1]
	s_mov_b32 s12, 0x42280000
	s_mov_b32 s13, 0x422c0000
	v_pk_fma_f32 v[54:55], v[92:93], s[12:13], v[6:7] op_sel_hi:[0,1,1]
	s_mov_b32 s12, 0x42400000
	s_mov_b32 s13, 0x42440000
	v_max3_f32 v0, v84, v48, v49
	v_pk_fma_f32 v[56:57], v[92:93], s[12:13], v[8:9] op_sel_hi:[0,1,1]
	s_mov_b32 s12, 0x42480000
	v_max3_f32 v0, v0, v50, v51
	s_mov_b32 s13, 0x424c0000
	v_max3_f32 v0, v0, v52, v53
	v_pk_fma_f32 v[58:59], v[92:93], s[12:13], v[10:11] op_sel_hi:[0,1,1]
	s_mov_b32 s12, 0x42600000
	v_max3_f32 v0, v0, v54, v55
	s_mov_b32 s13, 0x42640000
	v_max3_f32 v0, v0, v56, v57
	v_pk_fma_f32 v[60:61], v[92:93], s[12:13], v[12:13] op_sel_hi:[0,1,1]
	s_mov_b32 s12, 0x42680000
	v_max3_f32 v0, v0, v58, v59
	s_mov_b32 s13, 0x426c0000
	v_max3_f32 v0, v0, v60, v61
	v_pk_fma_f32 v[62:63], v[92:93], s[12:13], v[14:15] op_sel_hi:[0,1,1]
	v_max3_f32 v84, v0, v62, v63
	s_branch .LBB0_1136

.LBB0_1136:
	s_cmp_gt_u32 s4, 63
	s_cselect_b64 s[12:13], -1, 0
	s_cmp_lt_u32 s4, 64
	v_mov_b32_e32 v64, 0xf149f2ca
	s_cbranch_scc1 .LBB0_1138
	ds_read_b128 v[220:223], v163 offset:16384
	ds_read_b128 v[224:227], v164 offset:16384
	ds_read_b128 v[228:231], v165 offset:16384
	ds_read_b128 v[232:235], v166 offset:16384
	ds_read_b128 v[236:239], v167 offset:16384
	ds_read_b128 v[240:243], v168 offset:16384
	ds_read_b128 v[244:247], v169 offset:16384
	ds_read_b128 v[248:251], v170 offset:16384
	s_mov_b32 s14, 0x42800000
	s_mov_b32 s15, 0x42820000
	s_waitcnt vmcnt(7) lgkmcnt(7)
	v_mfma_f32_32x32x16_bf16 v[0:15], v[220:223], v[44:47], 0
	s_waitcnt vmcnt(6) lgkmcnt(6)
	v_mfma_f32_32x32x16_bf16 v[0:15], v[224:227], v[40:43], v[0:15]
	s_waitcnt vmcnt(5) lgkmcnt(5)
	v_mfma_f32_32x32x16_bf16 v[0:15], v[228:231], v[36:39], v[0:15]
	s_waitcnt vmcnt(4) lgkmcnt(4)
	v_mfma_f32_32x32x16_bf16 v[0:15], v[232:235], v[32:35], v[0:15]
	s_waitcnt vmcnt(3) lgkmcnt(3)
	v_mfma_f32_32x32x16_bf16 v[0:15], v[236:239], v[28:31], v[0:15]
	s_waitcnt vmcnt(2) lgkmcnt(2)
	v_mfma_f32_32x32x16_bf16 v[0:15], v[240:243], v[24:27], v[0:15]
	s_waitcnt vmcnt(1) lgkmcnt(1)
	v_mfma_f32_32x32x16_bf16 v[0:15], v[244:247], v[20:23], v[0:15]
	s_waitcnt vmcnt(0) lgkmcnt(0)
	v_mfma_f32_32x32x16_bf16 v[0:15], v[248:251], v[16:19], v[0:15]
	s_nop 11
	v_pk_fma_f32 v[64:65], v[92:93], s[14:15], v[0:1] op_sel_hi:[0,1,1]
	s_mov_b32 s14, 0x42840000
	s_mov_b32 s15, 0x42860000
	v_pk_fma_f32 v[66:67], v[92:93], s[14:15], v[2:3] op_sel_hi:[0,1,1]
	s_mov_b32 s14, 0x42900000
	s_mov_b32 s15, 0x42920000
	v_pk_fma_f32 v[68:69], v[92:93], s[14:15], v[4:5] op_sel_hi:[0,1,1]
	s_mov_b32 s14, 0x42940000
	s_mov_b32 s15, 0x42960000
	v_pk_fma_f32 v[70:71], v[92:93], s[14:15], v[6:7] op_sel_hi:[0,1,1]
	s_mov_b32 s14, 0x42a00000
	s_mov_b32 s15, 0x42a20000
	v_max3_f32 v0, v84, v64, v65
	v_pk_fma_f32 v[72:73], v[92:93], s[14:15], v[8:9] op_sel_hi:[0,1,1]
	s_mov_b32 s14, 0x42a40000
	v_max3_f32 v0, v0, v66, v67
	s_mov_b32 s15, 0x42a60000
	v_max3_f32 v0, v0, v68, v69
	v_pk_fma_f32 v[74:75], v[92:93], s[14:15], v[10:11] op_sel_hi:[0,1,1]
	s_mov_b32 s14, 0x42b00000
	v_max3_f32 v0, v0, v70, v71
	s_mov_b32 s15, 0x42b20000
	v_max3_f32 v0, v0, v72, v73
	v_pk_fma_f32 v[76:77], v[92:93], s[14:15], v[12:13] op_sel_hi:[0,1,1]
	s_mov_b32 s14, 0x42b40000
	v_max3_f32 v0, v0, v74, v75
	s_mov_b32 s15, 0x42b60000
	v_max3_f32 v0, v0, v76, v77
	v_pk_fma_f32 v[78:79], v[92:93], s[14:15], v[14:15] op_sel_hi:[0,1,1]
	v_max3_f32 v84, v0, v78, v79
	s_branch .LBB0_1139

.LBB0_1139:
	s_cmp_lg_u32 s4, 0
	s_cselect_b64 s[14:15], -1, 0
	s_and_b64 vcc, exec, s[14:15]
	s_cbranch_vccz .LBB0_1144
	ds_read_b128 v[220:223], v163 offset:24576
	ds_read_b128 v[224:227], v164 offset:24576
	ds_read_b128 v[228:231], v165 offset:24576
	ds_read_b128 v[232:235], v166 offset:24576
	ds_read_b128 v[236:239], v167 offset:24576
	ds_read_b128 v[240:243], v168 offset:24576
	ds_read_b128 v[244:247], v169 offset:24576
	ds_read_b128 v[248:251], v170 offset:24576
	s_mov_b32 s96, 0x42c00000
	s_mov_b32 s97, 0x42c20000
	s_waitcnt vmcnt(7) lgkmcnt(7)
	v_mfma_f32_32x32x16_bf16 v[0:15], v[220:223], v[44:47], 0
	s_waitcnt vmcnt(6) lgkmcnt(6)
	v_mfma_f32_32x32x16_bf16 v[0:15], v[224:227], v[40:43], v[0:15]
	s_waitcnt vmcnt(5) lgkmcnt(5)
	v_mfma_f32_32x32x16_bf16 v[0:15], v[228:231], v[36:39], v[0:15]
	s_waitcnt vmcnt(4) lgkmcnt(4)
	v_mfma_f32_32x32x16_bf16 v[0:15], v[232:235], v[32:35], v[0:15]
	s_waitcnt vmcnt(3) lgkmcnt(3)
	v_mfma_f32_32x32x16_bf16 v[0:15], v[236:239], v[28:31], v[0:15]
	s_waitcnt vmcnt(2) lgkmcnt(2)
	v_mfma_f32_32x32x16_bf16 v[0:15], v[240:243], v[24:27], v[0:15]
	s_waitcnt vmcnt(1) lgkmcnt(1)
	v_mfma_f32_32x32x16_bf16 v[0:15], v[244:247], v[20:23], v[0:15]
	s_waitcnt vmcnt(0) lgkmcnt(0)
	v_mfma_f32_32x32x16_bf16 v[0:15], v[248:251], v[16:19], v[0:15]
	s_nop 11
	v_pk_fma_f32 v[80:81], v[92:93], s[96:97], v[0:1] op_sel_hi:[0,1,1]
	s_mov_b32 s96, 0x42c40000
	s_mov_b32 s97, 0x42c60000
	v_pk_fma_f32 v[82:83], v[92:93], s[96:97], v[2:3] op_sel_hi:[0,1,1]
	s_mov_b32 s96, 0x42d00000
	s_mov_b32 s97, 0x42d20000
	v_pk_fma_f32 v[86:87], v[92:93], s[96:97], v[4:5] op_sel_hi:[0,1,1]
	s_mov_b32 s96, 0x42d40000
	s_mov_b32 s97, 0x42d60000
	v_pk_fma_f32 v[88:89], v[92:93], s[96:97], v[6:7] op_sel_hi:[0,1,1]
	s_mov_b32 s96, 0x42e00000
	s_mov_b32 s97, 0x42e20000
	v_max3_f32 v0, v84, v80, v81
	v_pk_fma_f32 v[90:91], v[92:93], s[96:97], v[8:9] op_sel_hi:[0,1,1]
	s_mov_b32 s96, 0x42e40000
	v_max3_f32 v0, v0, v82, v83
	s_mov_b32 s97, 0x42e60000
	v_max3_f32 v0, v0, v86, v87
	v_pk_fma_f32 v[94:95], v[92:93], s[96:97], v[10:11] op_sel_hi:[0,1,1]
	s_mov_b32 s96, 0x42f00000
	v_max3_f32 v0, v0, v88, v89
	s_mov_b32 s97, 0x42f20000
	v_max3_f32 v0, v0, v90, v91
	v_pk_fma_f32 v[96:97], v[92:93], s[96:97], v[12:13] op_sel_hi:[0,1,1]
	s_mov_b32 s96, 0x42f40000
	v_max3_f32 v0, v0, v94, v95
	s_mov_b32 s97, 0x42f60000
	v_max3_f32 v0, v0, v96, v97
	v_pk_fma_f32 v[98:99], v[92:93], s[96:97], v[14:15] op_sel_hi:[0,1,1]
	v_max3_f32 v115, v0, v98, v99
	s_cbranch_execnz .LBB0_1142

.LBB0_1142:
	ds_read_b128 v[220:223], v163 offset:32768
	ds_read_b128 v[224:227], v164 offset:32768
	ds_read_b128 v[228:231], v165 offset:32768
	ds_read_b128 v[232:235], v166 offset:32768
	ds_read_b128 v[236:239], v167 offset:32768
	ds_read_b128 v[240:243], v168 offset:32768
	ds_read_b128 v[244:247], v169 offset:32768
	ds_read_b128 v[248:251], v170 offset:32768
	s_movk_i32 s65, 0x7f
	v_cmp_lt_i32_e32 vcc, s65, v93
	s_movk_i32 s65, 0x80
	s_waitcnt vmcnt(7) lgkmcnt(7)
	v_mfma_f32_32x32x16_bf16 v[0:15], v[220:223], v[44:47], 0
	s_waitcnt vmcnt(6) lgkmcnt(6)
	v_mfma_f32_32x32x16_bf16 v[0:15], v[224:227], v[40:43], v[0:15]
	s_waitcnt vmcnt(5) lgkmcnt(5)
	v_mfma_f32_32x32x16_bf16 v[0:15], v[228:231], v[36:39], v[0:15]
	s_waitcnt vmcnt(4) lgkmcnt(4)
	v_mfma_f32_32x32x16_bf16 v[0:15], v[232:235], v[32:35], v[0:15]
	s_waitcnt vmcnt(3) lgkmcnt(3)
	v_mfma_f32_32x32x16_bf16 v[0:15], v[236:239], v[28:31], v[0:15]
	s_waitcnt vmcnt(2) lgkmcnt(2)
	v_mfma_f32_32x32x16_bf16 v[0:15], v[240:243], v[24:27], v[0:15]
	s_waitcnt vmcnt(1) lgkmcnt(1)
	v_mfma_f32_32x32x16_bf16 v[0:15], v[244:247], v[20:23], v[0:15]
	s_waitcnt vmcnt(0) lgkmcnt(0)
	v_mfma_f32_32x32x16_bf16 v[0:15], v[248:251], v[16:19], v[0:15]
	s_nop 11
	v_fmamk_f32 v0, v92, 0x43000000, v0
	v_cndmask_b32_e32 v116, v175, v0, vcc
	v_cmp_lt_i32_e32 vcc, s65, v93
	v_fmamk_f32 v0, v92, 0x43010000, v1
	v_fmamk_f32 v1, v92, 0x43020000, v2
	v_cndmask_b32_e32 v117, v175, v0, vcc
	v_cmp_lt_i32_e32 vcc, s67, v93
	s_movk_i32 s65, 0x82
	v_max3_f32 v0, v115, v116, v117
	v_cndmask_b32_e32 v118, v175, v1, vcc
	v_cmp_lt_i32_e32 vcc, s65, v93
	v_fmamk_f32 v1, v92, 0x43030000, v3
	s_movk_i32 s65, 0x87
	v_cndmask_b32_e32 v142, v175, v1, vcc
	v_cmp_lt_i32_e32 vcc, s65, v93
	v_fmamk_f32 v1, v92, 0x43080000, v4
	s_movk_i32 s65, 0x88
	v_cndmask_b32_e32 v143, v175, v1, vcc
	v_cmp_lt_i32_e32 vcc, s65, v93
	v_fmamk_f32 v1, v92, 0x43090000, v5
	s_movk_i32 s65, 0x89
	v_cndmask_b32_e32 v192, v175, v1, vcc
	v_cmp_lt_i32_e32 vcc, s65, v93
	v_fmamk_f32 v1, v92, 0x430a0000, v6
	s_movk_i32 s65, 0x8a
	v_cndmask_b32_e32 v193, v175, v1, vcc
	v_cmp_lt_i32_e32 vcc, s65, v93
	v_fmamk_f32 v1, v92, 0x430b0000, v7
	s_movk_i32 s65, 0x8f
	v_cndmask_b32_e32 v196, v175, v1, vcc
	v_cmp_lt_i32_e32 vcc, s65, v93
	v_fmamk_f32 v1, v92, 0x43100000, v8
	s_movk_i32 s65, 0x90
	v_cndmask_b32_e32 v197, v175, v1, vcc
	v_cmp_lt_i32_e32 vcc, s65, v93
	v_fmamk_f32 v1, v92, 0x43110000, v9
	s_movk_i32 s65, 0x91
	v_cndmask_b32_e32 v198, v175, v1, vcc
	v_cmp_lt_i32_e32 vcc, s65, v93
	v_fmamk_f32 v1, v92, 0x43120000, v10
	s_movk_i32 s65, 0x92
	v_max3_f32 v0, v0, v118, v142
	v_cndmask_b32_e32 v201, v175, v1, vcc
	v_cmp_lt_i32_e32 vcc, s65, v93
	v_fmamk_f32 v1, v92, 0x43130000, v11
	s_movk_i32 s65, 0x97
	v_max3_f32 v0, v0, v143, v192
	v_cndmask_b32_e32 v203, v175, v1, vcc
	v_cmp_lt_i32_e32 vcc, s65, v93
	v_fmamk_f32 v1, v92, 0x43180000, v12
	s_movk_i32 s65, 0x98
	v_max3_f32 v0, v0, v193, v196
	v_cndmask_b32_e32 v217, v175, v1, vcc
	v_cmp_lt_i32_e32 vcc, s65, v93
	v_fmamk_f32 v1, v92, 0x43190000, v13
	s_movk_i32 s65, 0x99
	v_max3_f32 v0, v0, v197, v198
	v_cndmask_b32_e32 v218, v175, v1, vcc
	v_cmp_lt_i32_e32 vcc, s65, v93
	v_fmamk_f32 v1, v92, 0x431a0000, v14
	s_movk_i32 s65, 0x9a
	v_max3_f32 v0, v0, v201, v203
	v_cndmask_b32_e32 v219, v175, v1, vcc
	v_cmp_lt_i32_e32 vcc, s65, v93
	v_fmac_f32_e32 v15, 0x431b0000, v92
	v_max3_f32 v0, v0, v217, v218
	v_cndmask_b32_e32 v252, v175, v15, vcc
	v_max3_f32 v115, v0, v219, v252
	v_fmac_f32_e32 v115, v92, v159
	v_mov_b32_e32 v119, v115
	s_nop 1
	v_permlane32_swap_b32_e32 v115, v119
	s_addk_i32 s61, 0xff80
	s_ashr_i32 s65, s61, 31
	s_add_u32 s96, s61, s45
	s_addc_u32 s97, s65, 0
	s_lshr_b64 s[96:97], s[96:97], 5
	s_lshl_b64 vcc, s[96:97], s53
	s_lshl_b32 s96, s44, 7
	s_ashr_i32 s97, s96, 31
	s_add_u32 s44, vcc_lo, s96
	s_addc_u32 s45, vcc_hi, s97
	v_lshl_add_u64 v[0:1], s[44:45], 0, v[130:131]
	v_lshlrev_b64 v[0:1], 6, v[0:1]
	s_cmp_lg_u32 s5, 0
	s_cselect_b64 vcc, -1, 0
	s_cmp_eq_u32 s5, 0
	v_lshl_add_u64 v[40:41], v[134:135], 0, v[0:1]
	s_cbranch_scc1 .LBB0_1145
	global_load_dwordx4 v[0:3], v[40:41], off
	s_branch .LBB0_1146
